# W1: kv-GEMM V^T epilogue pairs adjacent-key lanes via DPP+v_perm, 64 short stores -> 32 dword stores per wave
# baseline (speedup 1.0000x reference)
.LBB0_170:
	v_and_or_b32 v138, v132, 15, s78
	v_ashrrev_i32_e32 v132, 2, v132
	s_lshl_b32 s30, s15, 7
	v_and_b32_e32 v134, -4, v132
	v_add_u32_e32 v132, s26, v138
	s_ashr_i32 s31, s30, 31
	s_lshl_b64 s[62:63], s[18:19], 1
	v_ashrrev_i32_e32 v133, 31, v132
	s_add_u32 s34, s34, s62
	v_lshlrev_b64 v[140:141], 10, v[132:133]
	s_addc_u32 s35, s35, s63
	v_lshl_add_u64 v[140:141], s[4:5], 0, v[140:141]
	s_lshl_b64 s[30:31], s[30:31], 1
	v_ashrrev_i32_e32 v135, 31, v134
	v_lshl_add_u64 v[140:141], v[140:141], 0, s[30:31]
	s_mov_b32 s15, s19
	v_add_u32_e32 v142, s80, v134
	v_lshl_add_u64 v[140:141], v[140:141], 0, s[14:15]
	v_lshlrev_b64 v[134:135], 1, v[134:135]
	v_lshl_add_u64 v[140:141], v[140:141], 0, v[134:135]
	v_cvt_pk_bf16_f32 v122, v122, v123
	v_cvt_pk_bf16_f32 v123, v124, v125
	flat_store_dwordx2 v[140:141], v[122:123]
	v_cvt_pk_bf16_f32 v118, v118, v119
	v_cvt_pk_bf16_f32 v119, v120, v121
	v_ashrrev_i32_e32 v139, 31, v138
	flat_store_dwordx2 v[140:141], v[118:119] offset:32
	v_lshl_add_u64 v[138:139], v[138:139], 1, s[34:35]
	v_mad_i64_i32 v[118:119], s[26:27], s17, v142, 0
	v_lshl_add_u64 v[118:119], v[118:119], 1, v[138:139]
	s_lshl_b32 s18, s17, 1
	v_cvt_pk_bf16_f32 v122, v126, v127
	v_mbcnt_lo_u32_b32 v238, -1, 0
	v_mbcnt_hi_u32_b32 v238, -1, v238
	v_and_b32_e32 v238, 1, v238
	v_sub_u32_e32 v241, 0, v238
	v_and_b32_e32 v239, 0x6060606, v241
	v_xor_b32_e32 v239, 0x5040100, v239
	v_mov_b32_e32 v240, s18
	v_add_u32_e32 v240, -2, v240
	v_and_b32_e32 v240, v240, v241
	v_mov_b32_e32 v241, 0
	v_lshl_add_u64 v[120:121], v[118:119], 0, v[240:241]
	s_lshl_b32 s26, s17, 2
	s_mov_b32 s27, s19
	s_mul_i32 s34, s17, 6
	s_mov_b32 s35, s19
	v_cvt_pk_bf16_f32 v126, v128, v129
	s_nop 1
	v_mov_b32_dpp v238, v122 quad_perm:[1,0,3,2] row_mask:0xf bank_mask:0xf
	v_perm_b32 v122, v238, v122, v239
	flat_store_dword v[120:121], v122
	v_lshl_add_u64 v[122:123], v[118:119], 0, s[26:27]
	v_lshl_add_u64 v[124:125], v[122:123], 0, v[240:241]
	s_nop 1
	v_mov_b32_dpp v238, v126 quad_perm:[1,0,3,2] row_mask:0xf bank_mask:0xf
	v_perm_b32 v126, v238, v126, v239
	flat_store_dword v[124:125], v126
	v_cvt_pk_bf16_f32 v126, v114, v115
	v_add_u32_e32 v114, 16, v142
	v_mad_i64_i32 v[114:115], s[62:63], s17, v114, 0
	v_lshl_add_u64 v[114:115], v[114:115], 1, v[138:139]
	v_add_u32_e32 v138, 16, v132
	v_ashrrev_i32_e32 v139, 31, v138
	v_lshlrev_b64 v[138:139], 10, v[138:139]
	v_lshl_add_u64 v[138:139], s[4:5], 0, v[138:139]
	v_cvt_pk_bf16_f32 v133, v116, v117
	v_lshl_add_u64 v[116:117], v[114:115], 0, v[240:241]
	v_lshl_add_u64 v[138:139], v[138:139], 0, s[30:31]
	s_nop 1
	v_mov_b32_dpp v238, v126 quad_perm:[1,0,3,2] row_mask:0xf bank_mask:0xf
	v_perm_b32 v126, v238, v126, v239
	flat_store_dword v[116:117], v126
	v_lshl_add_u64 v[126:127], v[114:115], 0, s[26:27]
	v_lshl_add_u64 v[128:129], v[126:127], 0, v[240:241]
	v_lshl_add_u64 v[138:139], v[138:139], 0, s[14:15]
	s_nop 1
	v_mov_b32_dpp v238, v133 quad_perm:[1,0,3,2] row_mask:0xf bank_mask:0xf
	v_perm_b32 v133, v238, v133, v239
	flat_store_dword v[128:129], v133
	v_lshl_add_u64 v[138:139], v[138:139], 0, v[134:135]
	v_cvt_pk_bf16_f32 v102, v102, v103
	v_cvt_pk_bf16_f32 v103, v104, v105
	flat_store_dwordx2 v[138:139], v[102:103]
	v_cvt_pk_bf16_f32 v98, v98, v99
	v_cvt_pk_bf16_f32 v99, v100, v101
	flat_store_dwordx2 v[138:139], v[98:99] offset:32
	v_cvt_pk_bf16_f32 v98, v110, v111
	v_cvt_pk_bf16_f32 v99, v112, v113
	s_nop 1
	v_mov_b32_dpp v238, v98 quad_perm:[1,0,3,2] row_mask:0xf bank_mask:0xf
	v_perm_b32 v98, v238, v98, v239
	flat_store_dword v[120:121], v98 offset:32
	s_nop 1
	v_mov_b32_dpp v238, v99 quad_perm:[1,0,3,2] row_mask:0xf bank_mask:0xf
	v_perm_b32 v99, v238, v99, v239
	flat_store_dword v[124:125], v99 offset:32
	v_cvt_pk_bf16_f32 v98, v106, v107
	v_cvt_pk_bf16_f32 v99, v108, v109
	s_nop 1
	v_mov_b32_dpp v238, v98 quad_perm:[1,0,3,2] row_mask:0xf bank_mask:0xf
	v_perm_b32 v98, v238, v98, v239
	flat_store_dword v[116:117], v98 offset:32
	s_nop 1
	v_mov_b32_dpp v238, v99 quad_perm:[1,0,3,2] row_mask:0xf bank_mask:0xf
	v_perm_b32 v99, v238, v99, v239
	flat_store_dword v[128:129], v99 offset:32
	v_add_u32_e32 v98, 32, v132
	v_ashrrev_i32_e32 v99, 31, v98
	v_lshlrev_b64 v[98:99], 10, v[98:99]
	v_lshl_add_u64 v[98:99], s[4:5], 0, v[98:99]
	v_lshl_add_u64 v[98:99], v[98:99], 0, s[30:31]
	v_lshl_add_u64 v[98:99], v[98:99], 0, s[14:15]
	v_lshl_add_u64 v[98:99], v[98:99], 0, v[134:135]
	v_cvt_pk_bf16_f32 v86, v86, v87
	v_cvt_pk_bf16_f32 v87, v88, v89
	flat_store_dwordx2 v[98:99], v[86:87]
	v_cvt_pk_bf16_f32 v82, v82, v83
	v_cvt_pk_bf16_f32 v83, v84, v85
	flat_store_dwordx2 v[98:99], v[82:83] offset:32
	v_cvt_pk_bf16_f32 v82, v94, v95
	v_cvt_pk_bf16_f32 v83, v96, v97
	s_nop 1
	v_mov_b32_dpp v238, v82 quad_perm:[1,0,3,2] row_mask:0xf bank_mask:0xf
	v_perm_b32 v82, v238, v82, v239
	flat_store_dword v[120:121], v82 offset:64
	s_nop 1
	v_mov_b32_dpp v238, v83 quad_perm:[1,0,3,2] row_mask:0xf bank_mask:0xf
	v_perm_b32 v83, v238, v83, v239
	flat_store_dword v[124:125], v83 offset:64
	v_cvt_pk_bf16_f32 v82, v90, v91
	v_cvt_pk_bf16_f32 v83, v92, v93
	s_nop 1
	v_mov_b32_dpp v238, v82 quad_perm:[1,0,3,2] row_mask:0xf bank_mask:0xf
	v_perm_b32 v82, v238, v82, v239
	flat_store_dword v[116:117], v82 offset:64
	s_nop 1
	v_mov_b32_dpp v238, v83 quad_perm:[1,0,3,2] row_mask:0xf bank_mask:0xf
	v_perm_b32 v83, v238, v83, v239
	flat_store_dword v[128:129], v83 offset:64
	v_add_u32_e32 v82, 48, v132
	v_ashrrev_i32_e32 v83, 31, v82
	v_lshlrev_b64 v[82:83], 10, v[82:83]
	v_lshl_add_u64 v[82:83], s[4:5], 0, v[82:83]
	v_lshl_add_u64 v[82:83], v[82:83], 0, s[30:31]
	v_lshl_add_u64 v[82:83], v[82:83], 0, s[14:15]
	v_lshl_add_u64 v[82:83], v[82:83], 0, v[134:135]
	v_cvt_pk_bf16_f32 v52, v52, v53
	v_cvt_pk_bf16_f32 v53, v54, v55
	flat_store_dwordx2 v[82:83], v[52:53]
	v_cvt_pk_bf16_f32 v48, v48, v49
	v_cvt_pk_bf16_f32 v49, v50, v51
	flat_store_dwordx2 v[82:83], v[48:49] offset:32
	v_cvt_pk_bf16_f32 v48, v68, v69
	v_cvt_pk_bf16_f32 v49, v70, v71
	s_nop 1
	v_mov_b32_dpp v238, v48 quad_perm:[1,0,3,2] row_mask:0xf bank_mask:0xf
	v_perm_b32 v48, v238, v48, v239
	flat_store_dword v[120:121], v48 offset:96
	s_nop 1
	v_mov_b32_dpp v238, v49 quad_perm:[1,0,3,2] row_mask:0xf bank_mask:0xf
	v_perm_b32 v49, v238, v49, v239
	flat_store_dword v[124:125], v49 offset:96
	v_cvt_pk_bf16_f32 v48, v60, v61
	v_cvt_pk_bf16_f32 v49, v62, v63
	s_nop 1
	v_mov_b32_dpp v238, v48 quad_perm:[1,0,3,2] row_mask:0xf bank_mask:0xf
	v_perm_b32 v48, v238, v48, v239
	flat_store_dword v[116:117], v48 offset:96
	s_nop 1
	v_mov_b32_dpp v238, v49 quad_perm:[1,0,3,2] row_mask:0xf bank_mask:0xf
	v_perm_b32 v49, v238, v49, v239
	flat_store_dword v[128:129], v49 offset:96
	v_add_u32_e32 v48, 0x80, v132
	v_ashrrev_i32_e32 v49, 31, v48
	v_lshlrev_b64 v[48:49], 10, v[48:49]
	v_lshl_add_u64 v[48:49], s[4:5], 0, v[48:49]
	v_lshl_add_u64 v[48:49], v[48:49], 0, s[30:31]
	v_lshl_add_u64 v[48:49], v[48:49], 0, s[14:15]
	v_lshl_add_u64 v[48:49], v[48:49], 0, v[134:135]
	v_cvt_pk_bf16_f32 v50, v64, v65
	v_cvt_pk_bf16_f32 v51, v66, v67
	flat_store_dwordx2 v[48:49], v[50:51]
	v_cvt_pk_bf16_f32 v50, v56, v57
	v_cvt_pk_bf16_f32 v51, v58, v59
	flat_store_dwordx2 v[48:49], v[50:51] offset:32
	v_cvt_pk_bf16_f32 v48, v76, v77
	v_cvt_pk_bf16_f32 v49, v78, v79
	s_nop 1
	v_mov_b32_dpp v238, v48 quad_perm:[1,0,3,2] row_mask:0xf bank_mask:0xf
	v_perm_b32 v48, v238, v48, v239
	flat_store_dword v[120:121], v48 offset:256
	s_nop 1
	v_mov_b32_dpp v238, v49 quad_perm:[1,0,3,2] row_mask:0xf bank_mask:0xf
	v_perm_b32 v49, v238, v49, v239
	flat_store_dword v[124:125], v49 offset:256
	v_cvt_pk_bf16_f32 v48, v72, v73
	v_cvt_pk_bf16_f32 v49, v74, v75
	s_nop 1
	v_mov_b32_dpp v238, v48 quad_perm:[1,0,3,2] row_mask:0xf bank_mask:0xf
	v_perm_b32 v48, v238, v48, v239
	flat_store_dword v[116:117], v48 offset:256
	s_nop 1
	v_mov_b32_dpp v238, v49 quad_perm:[1,0,3,2] row_mask:0xf bank_mask:0xf
	v_perm_b32 v49, v238, v49, v239
	flat_store_dword v[128:129], v49 offset:256
	v_add_u32_e32 v48, 0x90, v132
	v_ashrrev_i32_e32 v49, 31, v48
	v_lshlrev_b64 v[48:49], 10, v[48:49]
	v_lshl_add_u64 v[48:49], s[4:5], 0, v[48:49]
	v_lshl_add_u64 v[48:49], v[48:49], 0, s[30:31]
	v_lshl_add_u64 v[48:49], v[48:49], 0, s[14:15]
	v_lshl_add_u64 v[48:49], v[48:49], 0, v[134:135]
	v_cvt_pk_bf16_f32 v36, v36, v37
	v_cvt_pk_bf16_f32 v37, v38, v39
	flat_store_dwordx2 v[48:49], v[36:37]
	v_cvt_pk_bf16_f32 v32, v32, v33
	v_cvt_pk_bf16_f32 v33, v34, v35
	flat_store_dwordx2 v[48:49], v[32:33] offset:32
	v_cvt_pk_bf16_f32 v32, v44, v45
	v_cvt_pk_bf16_f32 v33, v46, v47
	s_nop 1
	v_mov_b32_dpp v238, v32 quad_perm:[1,0,3,2] row_mask:0xf bank_mask:0xf
	v_perm_b32 v32, v238, v32, v239
	flat_store_dword v[120:121], v32 offset:288
	s_nop 1
	v_mov_b32_dpp v238, v33 quad_perm:[1,0,3,2] row_mask:0xf bank_mask:0xf
	v_perm_b32 v33, v238, v33, v239
	flat_store_dword v[124:125], v33 offset:288
	v_cvt_pk_bf16_f32 v32, v40, v41
	v_cvt_pk_bf16_f32 v33, v42, v43
	s_nop 1
	v_mov_b32_dpp v238, v32 quad_perm:[1,0,3,2] row_mask:0xf bank_mask:0xf
	v_perm_b32 v32, v238, v32, v239
	flat_store_dword v[116:117], v32 offset:288
	s_nop 1
	v_mov_b32_dpp v238, v33 quad_perm:[1,0,3,2] row_mask:0xf bank_mask:0xf
	v_perm_b32 v33, v238, v33, v239
	flat_store_dword v[128:129], v33 offset:288
	v_add_u32_e32 v32, 0xa0, v132
	v_ashrrev_i32_e32 v33, 31, v32
	v_lshlrev_b64 v[32:33], 10, v[32:33]
	v_lshl_add_u64 v[32:33], s[4:5], 0, v[32:33]
	v_lshl_add_u64 v[32:33], v[32:33], 0, s[30:31]
	v_lshl_add_u64 v[32:33], v[32:33], 0, s[14:15]
	v_lshl_add_u64 v[32:33], v[32:33], 0, v[134:135]
	v_cvt_pk_bf16_f32 v20, v20, v21
	v_cvt_pk_bf16_f32 v21, v22, v23
	flat_store_dwordx2 v[32:33], v[20:21]
	v_cvt_pk_bf16_f32 v16, v16, v17
	v_cvt_pk_bf16_f32 v17, v18, v19
	flat_store_dwordx2 v[32:33], v[16:17] offset:32
	v_cvt_pk_bf16_f32 v16, v28, v29
	v_cvt_pk_bf16_f32 v17, v30, v31
	s_nop 1
	v_mov_b32_dpp v238, v16 quad_perm:[1,0,3,2] row_mask:0xf bank_mask:0xf
	v_perm_b32 v16, v238, v16, v239
	flat_store_dword v[120:121], v16 offset:320
	s_nop 1
	v_mov_b32_dpp v238, v17 quad_perm:[1,0,3,2] row_mask:0xf bank_mask:0xf
	v_perm_b32 v17, v238, v17, v239
	flat_store_dword v[124:125], v17 offset:320
	v_cvt_pk_bf16_f32 v16, v24, v25
	v_cvt_pk_bf16_f32 v17, v26, v27
	s_nop 1
	v_mov_b32_dpp v238, v16 quad_perm:[1,0,3,2] row_mask:0xf bank_mask:0xf
	v_perm_b32 v16, v238, v16, v239
	flat_store_dword v[116:117], v16 offset:320
	s_nop 1
	v_mov_b32_dpp v238, v17 quad_perm:[1,0,3,2] row_mask:0xf bank_mask:0xf
	v_perm_b32 v17, v238, v17, v239
	flat_store_dword v[128:129], v17 offset:320
	v_add_u32_e32 v16, 0xb0, v132
	v_ashrrev_i32_e32 v17, 31, v16
	v_lshlrev_b64 v[16:17], 10, v[16:17]
	v_lshl_add_u64 v[16:17], s[4:5], 0, v[16:17]
	v_lshl_add_u64 v[16:17], v[16:17], 0, s[30:31]
	v_lshl_add_u64 v[16:17], v[16:17], 0, s[14:15]
	v_lshl_add_u64 v[16:17], v[16:17], 0, v[134:135]
	v_cvt_pk_bf16_f32 v4, v4, v5
	v_cvt_pk_bf16_f32 v5, v6, v7
	flat_store_dwordx2 v[16:17], v[4:5]
	v_cvt_pk_bf16_f32 v0, v0, v1
	v_cvt_pk_bf16_f32 v1, v2, v3
	flat_store_dwordx2 v[16:17], v[0:1] offset:32
	v_cvt_pk_bf16_f32 v0, v12, v13
	v_cvt_pk_bf16_f32 v1, v14, v15
	s_nop 1
	v_mov_b32_dpp v238, v0 quad_perm:[1,0,3,2] row_mask:0xf bank_mask:0xf
	v_perm_b32 v0, v238, v0, v239
	flat_store_dword v[120:121], v0 offset:352
	s_nop 1
	v_mov_b32_dpp v238, v1 quad_perm:[1,0,3,2] row_mask:0xf bank_mask:0xf
	v_perm_b32 v1, v238, v1, v239
	flat_store_dword v[124:125], v1 offset:352
	v_cvt_pk_bf16_f32 v0, v8, v9
	v_cvt_pk_bf16_f32 v1, v10, v11
	s_nop 1
	v_mov_b32_dpp v238, v0 quad_perm:[1,0,3,2] row_mask:0xf bank_mask:0xf
	v_perm_b32 v0, v238, v0, v239
	flat_store_dword v[116:117], v0 offset:352
	s_nop 1
	v_mov_b32_dpp v238, v1 quad_perm:[1,0,3,2] row_mask:0xf bank_mask:0xf
	v_perm_b32 v1, v238, v1, v239
	flat_store_dword v[128:129], v1 offset:352
	s_andn2_b64 vcc, exec, s[36:37]
	s_mov_b64 s[30:31], -1
	s_cbranch_vccnz .LBB0_157
	s_andn2_b64 vcc, exec, s[0:1]
	s_cbranch_vccnz .LBB0_156
	s_barrier
	s_branch .LBB0_156
